# M2: per-step prefetch block issued after the segment's MFMAs / v_new write (just before the first LDS barrier) instead of at the segment head
# baseline (speedup 1.0000x reference)
.Lm2_topA:
	v_mov_b64_e32 v[66:67], v[14:15]
	v_mov_b64_e32 v[64:65], v[12:13]
	v_mov_b64_e32 v[70:71], v[10:11]
	v_mov_b64_e32 v[74:75], v[6:7]
	v_mov_b64_e32 v[78:79], v[2:3]
	v_mov_b64_e32 v[68:69], v[8:9]
	v_mov_b64_e32 v[72:73], v[4:5]
	v_mov_b64_e32 v[76:77], v[0:1]
	v_add_u32_e32 v142, v81, v109
	ds_read_b128 v[162:165], v142
	ds_read_b128 v[166:169], v142 offset:4352
	ds_read_b128 v[172:175], v142 offset:64
	ds_read_b128 v[176:179], v142 offset:4416
	s_andn2_b64 vcc, exec, s[2:3]
	s_waitcnt lgkmcnt(2)
	v_mfma_f32_16x16x32_bf16 v[134:137], v[76:79], v[162:165], 0
	v_mfma_f32_16x16x32_bf16 v[138:141], v[76:79], v[166:169], 0
	s_nop 2
	ds_read_b128 v[162:165], v142 offset:128
	ds_read_b128 v[166:169], v142 offset:4480
	s_waitcnt lgkmcnt(2)
	v_mfma_f32_16x16x32_bf16 v[134:137], v[72:75], v[172:175], v[134:137]
	v_mfma_f32_16x16x32_bf16 v[138:141], v[72:75], v[176:179], v[138:141]
	s_nop 2
	ds_read_b128 v[172:175], v142 offset:192
	ds_read_b128 v[176:179], v142 offset:4544
	s_waitcnt lgkmcnt(2)
	v_mfma_f32_16x16x32_bf16 v[134:137], v[68:71], v[162:165], v[134:137]
	v_mfma_f32_16x16x32_bf16 v[138:141], v[68:71], v[166:169], v[138:141]
	s_waitcnt lgkmcnt(0)
	v_mfma_f32_16x16x32_bf16 v[72:75], v[64:67], v[172:175], v[134:137]
	v_mfma_f32_16x16x32_bf16 v[76:79], v[64:67], v[176:179], v[138:141]
	s_nop 7
	s_cbranch_vccnz .Lm2_179a
	s_waitcnt vmcnt(42)
	v_sub_f32_e32 v56, v56, v72
	s_waitcnt vmcnt(41)
	v_sub_f32_e32 v57, v57, v73
	v_cvt_pk_bf16_f32 v56, v56, v57
	s_waitcnt vmcnt(40)
	v_sub_f32_e32 v57, v58, v74
	s_waitcnt vmcnt(39)
	v_sub_f32_e32 v58, v59, v75
	v_cvt_pk_bf16_f32 v57, v57, v58
	ds_write_b64 v117, v[56:57] offset:8704
	s_waitcnt vmcnt(38)
	v_sub_f32_e32 v56, v60, v76
	s_waitcnt vmcnt(37)
	v_sub_f32_e32 v57, v61, v77
	v_cvt_pk_bf16_f32 v56, v56, v57
	s_waitcnt vmcnt(35)
	v_sub_f32_e32 v57, v62, v78
	s_waitcnt vmcnt(34)
	v_sub_f32_e32 v58, v63, v79
	v_cvt_pk_bf16_f32 v57, v57, v58
	ds_write_b64 v117, v[56:57] offset:11008
.Lm2_179a:
	s_add_i32 s56, s18, 1
	s_min_i32 s56, s56, 31
	s_add_u32 s14, s8, s56
	s_addc_u32 s15, s9, 0
	s_nop 0
	s_lshl_b64 s[20:21], s[14:15], 13
	s_lshl_b64 s[14:15], s[14:15], 14
	v_lshl_add_u64 v[12:13], v[82:83], 0, s[14:15]
	v_lshl_add_u64 v[48:49], v[84:85], 0, s[14:15]
	s_lshl_b64 s[14:15], s[56:57], 2
	s_add_u32 s14, s10, s14
	s_addc_u32 s15, s11, s15
	global_load_dwordx4 v[0:3], v[12:13], off
	global_load_dwordx4 v[4:7], v[12:13], off offset:64
	global_load_dwordx4 v[8:11], v[12:13], off offset:128
	global_load_dwordx4 v[12:15], v[12:13], off offset:192
	global_load_dwordx4 v[40:43], v[48:49], off
	global_load_dwordx4 v[48:51], v[48:49], off offset:64
	global_load_dword v101, v145, s[14:15]
	s_cmp_lg_u64 s[2:3], 0
	s_cbranch_scc1 .Lm2_skga
	v_lshl_add_u64 v[52:53], v[86:87], 0, s[20:21]
	global_load_dwordx4 v[44:47], v[52:53], off
	global_load_dwordx4 v[52:55], v[52:53], off offset:64
.Lm2_skga:
	s_cmp_eq_u64 s[2:3], 0
	s_cbranch_scc1 .Lm2_skua
	v_or_b32_e32 v246, s20, v171
	v_mov_b32_e32 v247, s21
	v_lshl_add_u64 v[246:247], v[246:247], 2, s[82:83]
	global_load_dwordx4 v[126:129], v[246:247], off
	global_load_dwordx4 v[130:133], v[246:247], off offset:64
.Lm2_skua:
	s_waitcnt lgkmcnt(0)
	s_barrier
	s_waitcnt vmcnt(38)
	v_add_u32_e32 v60, v81, v111
	ds_read_b128 v[68:71], v60 offset:8704
	ds_read_b128 v[56:59], v60 offset:8768
	ds_read_b128 v[64:67], v60 offset:11008
	s_waitcnt vmcnt(34)
	ds_read_b128 v[60:63], v60 offset:11072
	s_andn2_b64 vcc, exec, s[4:5]
	s_mov_b64 s[14:15], -1
	s_cbranch_vccnz .Lm2_181a
	s_mov_b64 s[14:15], 0

.Lm2_topB:
	v_mov_b64_e32 v[66:67], v[226:227]
	v_mov_b64_e32 v[64:65], v[224:225]
	v_mov_b64_e32 v[70:71], v[222:223]
	v_mov_b64_e32 v[74:75], v[218:219]
	v_mov_b64_e32 v[78:79], v[214:215]
	v_mov_b64_e32 v[68:69], v[220:221]
	v_mov_b64_e32 v[72:73], v[216:217]
	v_mov_b64_e32 v[76:77], v[212:213]
	v_add_u32_e32 v142, v81, v109
	ds_read_b128 v[162:165], v142
	ds_read_b128 v[166:169], v142 offset:4352
	ds_read_b128 v[172:175], v142 offset:64
	ds_read_b128 v[176:179], v142 offset:4416
	s_andn2_b64 vcc, exec, s[2:3]
	s_waitcnt lgkmcnt(2)
	v_mfma_f32_16x16x32_bf16 v[134:137], v[76:79], v[162:165], 0
	v_mfma_f32_16x16x32_bf16 v[138:141], v[76:79], v[166:169], 0
	s_nop 2
	ds_read_b128 v[162:165], v142 offset:128
	ds_read_b128 v[166:169], v142 offset:4480
	s_waitcnt lgkmcnt(2)
	v_mfma_f32_16x16x32_bf16 v[134:137], v[72:75], v[172:175], v[134:137]
	v_mfma_f32_16x16x32_bf16 v[138:141], v[72:75], v[176:179], v[138:141]
	s_nop 2
	ds_read_b128 v[172:175], v142 offset:192
	ds_read_b128 v[176:179], v142 offset:4544
	s_waitcnt lgkmcnt(2)
	v_mfma_f32_16x16x32_bf16 v[134:137], v[68:71], v[162:165], v[134:137]
	v_mfma_f32_16x16x32_bf16 v[138:141], v[68:71], v[166:169], v[138:141]
	s_waitcnt lgkmcnt(0)
	v_mfma_f32_16x16x32_bf16 v[72:75], v[64:67], v[172:175], v[134:137]
	v_mfma_f32_16x16x32_bf16 v[76:79], v[64:67], v[176:179], v[138:141]
	s_nop 7
	s_cbranch_vccnz .Lm2_179b
	s_waitcnt vmcnt(42)
	v_sub_f32_e32 v56, v56, v72
	s_waitcnt vmcnt(41)
	v_sub_f32_e32 v57, v57, v73
	v_cvt_pk_bf16_f32 v56, v56, v57
	s_waitcnt vmcnt(40)
	v_sub_f32_e32 v57, v58, v74
	s_waitcnt vmcnt(39)
	v_sub_f32_e32 v58, v59, v75
	v_cvt_pk_bf16_f32 v57, v57, v58
	ds_write_b64 v117, v[56:57] offset:8704
	s_waitcnt vmcnt(38)
	v_sub_f32_e32 v56, v60, v76
	s_waitcnt vmcnt(37)
	v_sub_f32_e32 v57, v61, v77
	v_cvt_pk_bf16_f32 v56, v56, v57
	s_waitcnt vmcnt(35)
	v_sub_f32_e32 v57, v62, v78
	s_waitcnt vmcnt(34)
	v_sub_f32_e32 v58, v63, v79
	v_cvt_pk_bf16_f32 v57, v57, v58
	ds_write_b64 v117, v[56:57] offset:11008
.Lm2_179b:
	s_add_i32 s56, s18, 1
	s_min_i32 s56, s56, 31
	s_add_u32 s14, s8, s56
	s_addc_u32 s15, s9, 0
	s_nop 0
	s_lshl_b64 s[20:21], s[14:15], 13
	s_lshl_b64 s[14:15], s[14:15], 14
	v_lshl_add_u64 v[224:225], v[82:83], 0, s[14:15]
	v_lshl_add_u64 v[236:237], v[84:85], 0, s[14:15]
	s_lshl_b64 s[14:15], s[56:57], 2
	s_add_u32 s14, s10, s14
	s_addc_u32 s15, s11, s15
	global_load_dwordx4 v[212:215], v[224:225], off
	global_load_dwordx4 v[216:219], v[224:225], off offset:64
	global_load_dwordx4 v[220:223], v[224:225], off offset:128
	global_load_dwordx4 v[224:227], v[224:225], off offset:192
	global_load_dwordx4 v[228:231], v[236:237], off
	global_load_dwordx4 v[236:239], v[236:237], off offset:64
	global_load_dword v143, v145, s[14:15]
	s_cmp_lg_u64 s[2:3], 0
	s_cbranch_scc1 .Lm2_skgb
	v_lshl_add_u64 v[242:243], v[86:87], 0, s[20:21]
	global_load_dwordx4 v[232:235], v[242:243], off
	global_load_dwordx4 v[242:245], v[242:243], off offset:64
.Lm2_skgb:
	s_cmp_eq_u64 s[2:3], 0
	s_cbranch_scc1 .Lm2_skub
	v_or_b32_e32 v246, s20, v171
	v_mov_b32_e32 v247, s21
	v_lshl_add_u64 v[246:247], v[246:247], 2, s[82:83]
	global_load_dwordx4 v[180:183], v[246:247], off
	global_load_dwordx4 v[184:187], v[246:247], off offset:64
.Lm2_skub:
	s_waitcnt lgkmcnt(0)
	s_barrier
	s_waitcnt vmcnt(38)
	v_add_u32_e32 v60, v81, v111
	ds_read_b128 v[68:71], v60 offset:8704
	ds_read_b128 v[56:59], v60 offset:8768
	ds_read_b128 v[64:67], v60 offset:11008
	s_waitcnt vmcnt(34)
	ds_read_b128 v[60:63], v60 offset:11072
	s_andn2_b64 vcc, exec, s[4:5]
	s_mov_b64 s[14:15], -1
	s_cbranch_vccnz .Lm2_181b
	s_mov_b64 s[14:15], 0
